# as v133 plus layer-0 P4b epilogue: the x_new (residual) stores are issued after the RMS panel poll instead of before the slot-store drain; same code size and byte phases
# speedup vs baseline: 1.0023x; 1.0023x over previous
.LBB0_1033:
	s_lshl_b32 s2, s19, 2
	s_add_i32 s2, s2, 0
	s_add_i32 s5, s2, 0x20800
	v_readlane_b32 s2, v253, 21
	v_readlane_b32 s3, v253, 22
	s_mov_b32 s14, s2
	v_readlane_b32 s2, v253, 24
	s_lshl_b32 s3, s2, 7
	s_or_b32 s3, s3, s18
	v_lshl_add_u32 v140, v143, 3, s3
	s_getreg_b32 s3, hwreg(HW_REG_HW_ID, 0, 6)
	s_lshl_b32 s4, s14, 8
	s_lshl_b32 s3, s3, 2
	s_and_b32 s3, s3, 0xfc
	s_add_i32 s6, s4, 0xfffff000
	s_add_i32 s3, s3, 0
	s_lshr_b32 s6, s6, 11
	s_add_i32 s3, s3, 0x20200
	s_add_i32 s6, s6, 1
	s_cmp_gt_i32 s14, 15
	v_mov_b32_e32 v128, s3
	s_mul_i32 s3, s40, 3
	s_cselect_b32 s17, s6, 0
	ds_read_b32 v138, v128
	s_add_u32 s3, s3, s17
	v_mov_b64_e32 v[128:129], s[10:11]
	v_mov_b32_e32 v130, 0x3000
	s_addc_u32 s12, 0, 0
	v_mad_u64_u32 v[128:129], s[6:7], s3, v130, v[128:129]
	v_mad_u32_u24 v129, s12, v130, v129
	v_ashrrev_i32_e32 v141, 31, v140
	v_lshl_add_u64 v[128:129], v[140:141], 2, v[128:129]
	s_mov_b32 s3, 0x102000
	v_add_co_u32_e32 v130, vcc, s3, v128
	s_mov_b64 s[6:7], 0x102000
	s_nop 0
	v_addc_co_u32_e32 v131, vcc, 0, v129, vcc
	v_mbcnt_lo_u32_b32 v136, -1, 0
	v_mbcnt_hi_u32_b32 v136, -1, v136
	global_load_dwordx4 v[132:135], v[130:131], off
	v_lshl_add_u64 v[128:129], v[128:129], 0, s[6:7]
	global_load_dwordx4 v[128:131], v[128:129], off offset:16
	v_cmp_eq_u32_e32 vcc, 0, v143
	s_waitcnt lgkmcnt(0)
	v_readfirstlane_b32 s3, v138
	s_waitcnt vmcnt(0)
	v_pk_fma_f32 v[2:3], v[126:127], v[134:135], v[2:3]
	v_pk_fma_f32 v[0:1], v[124:125], v[132:133], v[0:1]
	v_pk_fma_f32 v[4:5], v[120:121], v[128:129], v[4:5]
	v_mul_f32_e32 v120, v1, v1
	v_mul_f32_e32 v121, v3, v3
	v_pk_fma_f32 v[6:7], v[122:123], v[130:131], v[6:7]
	v_mul_f32_e32 v122, v5, v5
	v_fmac_f32_e32 v120, v0, v0
	v_fmac_f32_e32 v121, v2, v2
	v_mul_f32_e32 v123, v7, v7
	v_fmac_f32_e32 v122, v4, v4
	v_add_f32_e32 v120, v120, v121
	v_fmac_f32_e32 v123, v6, v6
	v_add_f32_e32 v120, v120, v122
	v_add_f32_e32 v121, v123, v120
	ds_swizzle_b32 v122, v121 offset:swizzle(SWAP,16)
	v_add_u32_e32 v120, s16, v142
	s_waitcnt lgkmcnt(0)
	v_add_f32_e32 v122, v121, v122
	v_mov_b32_e32 v123, v122
	s_nop 1
	v_permlane32_swap_b32_e32 v122, v123
	v_lshl_add_u32 v121, v120, 4, s5
	s_and_saveexec_b64 s[6:7], vcc
	v_add_f32_e32 v122, v122, v123
	ds_write_b32 v121, v122
	s_or_b64 exec, exec, s[6:7]
	v_pk_fma_f32 v[26:27], v[26:27], v[134:135], v[14:15]
	v_pk_fma_f32 v[24:25], v[24:25], v[132:133], v[12:13]
	v_pk_fma_f32 v[28:29], v[28:29], v[128:129], v[8:9]
	v_mul_f32_e32 v8, v25, v25
	v_mul_f32_e32 v9, v27, v27
	v_fmac_f32_e32 v8, v24, v24
	v_fmac_f32_e32 v9, v26, v26
	v_add_f32_e32 v8, v8, v9
	v_mul_f32_e32 v9, v29, v29
	v_pk_fma_f32 v[30:31], v[30:31], v[130:131], v[10:11]
	v_fmac_f32_e32 v9, v28, v28
	v_add_f32_e32 v8, v8, v9
	v_mul_f32_e32 v9, v31, v31
	v_fmac_f32_e32 v9, v30, v30
	v_add_f32_e32 v8, v9, v8
	ds_swizzle_b32 v9, v8 offset:swizzle(SWAP,16)
	s_waitcnt lgkmcnt(0)
	v_add_f32_e32 v8, v8, v9
	v_mov_b32_e32 v9, v8
	s_nop 1
	v_permlane32_swap_b32_e32 v8, v9
	s_and_saveexec_b64 s[6:7], vcc
	v_add_f32_e32 v8, v8, v9
	ds_write_b32 v121, v8 offset:256
	s_or_b64 exec, exec, s[6:7]
	v_pk_fma_f32 v[62:63], v[62:63], v[134:135], v[22:23]
	v_pk_fma_f32 v[60:61], v[60:61], v[132:133], v[20:21]
	v_mul_f32_e32 v9, v63, v63
	v_mul_f32_e32 v8, v61, v61
	v_pk_fma_f32 v[56:57], v[56:57], v[128:129], v[16:17]
	v_fmac_f32_e32 v8, v60, v60
	v_fmac_f32_e32 v9, v62, v62
	v_add_f32_e32 v8, v8, v9
	v_mul_f32_e32 v9, v57, v57
	v_pk_fma_f32 v[58:59], v[58:59], v[130:131], v[18:19]
	v_fmac_f32_e32 v9, v56, v56
	v_add_f32_e32 v8, v8, v9
	v_mul_f32_e32 v9, v59, v59
	v_fmac_f32_e32 v9, v58, v58
	v_add_f32_e32 v8, v9, v8
	ds_swizzle_b32 v9, v8 offset:swizzle(SWAP,16)
	s_waitcnt lgkmcnt(0)
	v_add_f32_e32 v8, v8, v9
	v_mov_b32_e32 v9, v8
	s_nop 1
	v_permlane32_swap_b32_e32 v8, v9
	s_and_saveexec_b64 s[6:7], vcc
	v_add_f32_e32 v8, v8, v9
	ds_write_b32 v121, v8 offset:512
	s_or_b64 exec, exec, s[6:7]
	v_pk_fma_f32 v[14:15], v[118:119], v[134:135], v[38:39]
	v_pk_fma_f32 v[12:13], v[116:117], v[132:133], v[36:37]
	v_mul_f32_e32 v17, v15, v15
	v_mul_f32_e32 v16, v13, v13
	v_pk_fma_f32 v[8:9], v[112:113], v[128:129], v[32:33]
	v_fmac_f32_e32 v16, v12, v12
	v_fmac_f32_e32 v17, v14, v14
	v_add_f32_e32 v16, v16, v17
	v_mul_f32_e32 v17, v9, v9
	v_pk_fma_f32 v[10:11], v[114:115], v[130:131], v[34:35]
	v_fmac_f32_e32 v17, v8, v8
	v_add_f32_e32 v16, v16, v17
	v_mul_f32_e32 v17, v11, v11
	v_fmac_f32_e32 v17, v10, v10
	v_add_f32_e32 v16, v17, v16
	ds_swizzle_b32 v17, v16 offset:swizzle(SWAP,16)
	s_waitcnt lgkmcnt(0)
	v_add_f32_e32 v16, v16, v17
	v_mov_b32_e32 v17, v16
	s_nop 1
	v_permlane32_swap_b32_e32 v16, v17
	s_and_saveexec_b64 s[6:7], vcc
	v_add_f32_e32 v16, v16, v17
	ds_write_b32 v121, v16 offset:768
	s_or_b64 exec, exec, s[6:7]
	v_pk_fma_f32 v[22:23], v[110:111], v[134:135], v[46:47]
	v_pk_fma_f32 v[20:21], v[108:109], v[132:133], v[44:45]
	v_mul_f32_e32 v33, v23, v23
	v_mul_f32_e32 v32, v21, v21
	v_pk_fma_f32 v[16:17], v[104:105], v[128:129], v[40:41]
	v_fmac_f32_e32 v32, v20, v20
	v_fmac_f32_e32 v33, v22, v22
	v_add_f32_e32 v32, v32, v33
	v_mul_f32_e32 v33, v17, v17
	v_pk_fma_f32 v[18:19], v[106:107], v[130:131], v[42:43]
	v_fmac_f32_e32 v33, v16, v16
	v_add_f32_e32 v32, v32, v33
	v_mul_f32_e32 v33, v19, v19
	v_fmac_f32_e32 v33, v18, v18
	v_add_f32_e32 v32, v33, v32
	ds_swizzle_b32 v33, v32 offset:swizzle(SWAP,16)
	s_waitcnt lgkmcnt(0)
	v_add_f32_e32 v32, v32, v33
	v_mov_b32_e32 v33, v32
	s_nop 1
	v_permlane32_swap_b32_e32 v32, v33
	s_and_saveexec_b64 s[6:7], vcc
	v_add_f32_e32 v32, v32, v33
	ds_write_b32 v121, v32 offset:2048
	s_or_b64 exec, exec, s[6:7]
	v_pk_fma_f32 v[38:39], v[102:103], v[134:135], v[54:55]
	v_pk_fma_f32 v[36:37], v[100:101], v[132:133], v[52:53]
	v_mul_f32_e32 v41, v39, v39
	v_mul_f32_e32 v40, v37, v37
	v_pk_fma_f32 v[32:33], v[96:97], v[128:129], v[48:49]
	v_fmac_f32_e32 v40, v36, v36
	v_fmac_f32_e32 v41, v38, v38
	v_add_f32_e32 v40, v40, v41
	v_mul_f32_e32 v41, v33, v33
	v_pk_fma_f32 v[34:35], v[98:99], v[130:131], v[50:51]
	v_fmac_f32_e32 v41, v32, v32
	v_add_f32_e32 v40, v40, v41
	v_mul_f32_e32 v41, v35, v35
	v_fmac_f32_e32 v41, v34, v34
	v_add_f32_e32 v40, v41, v40
	ds_swizzle_b32 v41, v40 offset:swizzle(SWAP,16)
	s_waitcnt lgkmcnt(0)
	v_add_f32_e32 v40, v40, v41
	v_mov_b32_e32 v41, v40
	s_nop 1
	v_permlane32_swap_b32_e32 v40, v41
	s_and_saveexec_b64 s[6:7], vcc
	v_add_f32_e32 v40, v40, v41
	ds_write_b32 v121, v40 offset:2304
	s_or_b64 exec, exec, s[6:7]
	v_pk_fma_f32 v[46:47], v[94:95], v[134:135], v[70:71]
	v_pk_fma_f32 v[44:45], v[92:93], v[132:133], v[68:69]
	v_mul_f32_e32 v49, v47, v47
	v_mul_f32_e32 v48, v45, v45
	v_pk_fma_f32 v[40:41], v[88:89], v[128:129], v[64:65]
	v_fmac_f32_e32 v48, v44, v44
	v_fmac_f32_e32 v49, v46, v46
	v_add_f32_e32 v48, v48, v49
	v_mul_f32_e32 v49, v41, v41
	v_pk_fma_f32 v[42:43], v[90:91], v[130:131], v[66:67]
	v_fmac_f32_e32 v49, v40, v40
	v_add_f32_e32 v48, v48, v49
	v_mul_f32_e32 v49, v43, v43
	v_fmac_f32_e32 v49, v42, v42
	v_add_f32_e32 v48, v49, v48
	ds_swizzle_b32 v49, v48 offset:swizzle(SWAP,16)
	s_waitcnt lgkmcnt(0)
	v_add_f32_e32 v48, v48, v49
	v_mov_b32_e32 v49, v48
	s_nop 1
	v_permlane32_swap_b32_e32 v48, v49
	s_and_saveexec_b64 s[6:7], vcc
	v_add_f32_e32 v48, v48, v49
	ds_write_b32 v121, v48 offset:2560
	s_or_b64 exec, exec, s[6:7]
	v_pk_fma_f32 v[54:55], v[86:87], v[134:135], v[78:79]
	v_pk_fma_f32 v[52:53], v[84:85], v[132:133], v[76:77]
	v_mul_f32_e32 v65, v55, v55
	v_mul_f32_e32 v64, v53, v53
	v_pk_fma_f32 v[48:49], v[80:81], v[128:129], v[72:73]
	v_fmac_f32_e32 v64, v52, v52
	v_fmac_f32_e32 v65, v54, v54
	v_add_f32_e32 v64, v64, v65
	v_mul_f32_e32 v65, v49, v49
	v_pk_fma_f32 v[50:51], v[82:83], v[130:131], v[74:75]
	v_fmac_f32_e32 v65, v48, v48
	v_add_f32_e32 v64, v64, v65
	v_mul_f32_e32 v65, v51, v51
	v_fmac_f32_e32 v65, v50, v50
	v_add_f32_e32 v64, v65, v64
	ds_swizzle_b32 v65, v64 offset:swizzle(SWAP,16)
	s_waitcnt lgkmcnt(0)
	v_add_f32_e32 v64, v64, v65
	v_mov_b32_e32 v65, v64
	s_nop 1
	v_permlane32_swap_b32_e32 v64, v65
	s_and_saveexec_b64 s[6:7], vcc
	v_add_f32_e32 v64, v64, v65
	ds_write_b32 v121, v64 offset:2816
	s_or_b64 exec, exec, s[6:7]
	v_add_u32_e32 v80, s4, v120
	v_ashrrev_i32_e32 v81, 31, v80

.LBB0_1067:
	s_or_b64 exec, exec, s[2:3]
	v_readlane_b32 s100, v253, 44
	v_readlane_b32 s101, v253, 45
	s_and_b64 vcc, exec, s[100:101]
	s_cbranch_vccz .Lmy_xn_skip
	v_lshlrev_b64 v[84:85], 12, v[80:81]
	v_lshl_add_u64 v[84:85], s[8:9], 0, v[84:85]
	v_lshl_add_u64 v[84:85], v[140:141], 2, v[84:85]
	v_add_co_u32_e32 v88, vcc, 0x10000, v84
	s_mov_b64 s[100:101], 0x10000
	s_nop 0
	v_addc_co_u32_e32 v89, vcc, 0, v85, vcc
	global_store_dwordx4 v[84:85], v[0:3], off
	global_store_dwordx4 v[84:85], v[4:7], off offset:16
	v_lshl_add_u64 v[86:87], v[84:85], 0, s[100:101]
	global_store_dwordx4 v[88:89], v[24:27], off
	global_store_dwordx4 v[86:87], v[28:31], off offset:16
	v_add_co_u32_e32 v88, vcc, 0x20000, v84
	s_mov_b64 s[100:101], 0x20000
	s_nop 0
	v_addc_co_u32_e32 v89, vcc, 0, v85, vcc
	v_lshl_add_u64 v[86:87], v[84:85], 0, s[100:101]
	global_store_dwordx4 v[88:89], v[60:63], off
	global_store_dwordx4 v[86:87], v[56:59], off offset:16
	v_add_co_u32_e32 v88, vcc, 0x30000, v84
	s_mov_b64 s[100:101], 0x30000
	s_nop 0
	v_addc_co_u32_e32 v89, vcc, 0, v85, vcc
	v_lshl_add_u64 v[86:87], v[84:85], 0, s[100:101]
	global_store_dwordx4 v[88:89], v[12:15], off
	global_store_dwordx4 v[86:87], v[8:11], off offset:16
	v_add_co_u32_e32 v88, vcc, 0x80000, v84
	s_mov_b64 s[100:101], 0x80000
	s_nop 0
	v_addc_co_u32_e32 v89, vcc, 0, v85, vcc
	v_lshl_add_u64 v[86:87], v[84:85], 0, s[100:101]
	global_store_dwordx4 v[88:89], v[20:23], off
	global_store_dwordx4 v[86:87], v[16:19], off offset:16
	v_add_co_u32_e32 v88, vcc, 0x90000, v84
	s_mov_b64 s[100:101], 0x90000
	s_nop 0
	v_addc_co_u32_e32 v89, vcc, 0, v85, vcc
	v_lshl_add_u64 v[86:87], v[84:85], 0, s[100:101]
	global_store_dwordx4 v[88:89], v[36:39], off
	global_store_dwordx4 v[86:87], v[32:35], off offset:16
	s_mov_b64 s[100:101], 0xa0000
	v_add_co_u32_e32 v88, vcc, 0xa0000, v84
	v_lshl_add_u64 v[86:87], v[84:85], 0, s[100:101]
	s_nop 0
	v_addc_co_u32_e32 v89, vcc, 0, v85, vcc
	s_mov_b64 s[100:101], 0xb0000
	global_store_dwordx4 v[88:89], v[44:47], off
	global_store_dwordx4 v[86:87], v[40:43], off offset:16
	v_lshl_add_u64 v[86:87], v[84:85], 0, s[100:101]
	v_add_co_u32_e32 v84, vcc, 0xb0000, v84
	s_nop 1
	v_addc_co_u32_e32 v85, vcc, 0, v85, vcc
	global_store_dwordx4 v[84:85], v[52:55], off
	global_store_dwordx4 v[86:87], v[48:51], off offset:16
.Lmy_xn_skip:
	s_barrier
	s_and_saveexec_b64 s[2:3], s[6:7]
	s_cbranch_execz .LBB0_1069
	v_readlane_b32 s4, v253, 34
	v_readlane_b32 s7, v253, 37
	s_and_b32 s45, s45, 0xffff
	s_mov_b32 s47, s7
	v_lshlrev_b32_e32 v65, 5, v64
	buffer_load_dwordx4 v[66:69], v65, s[44:47], 0 offen sc1
	buffer_load_dwordx4 v[70:73], v65, s[44:47], 0 offen offset:16 sc1
	s_mov_b32 s4, 0xf800000
	v_readlane_b32 s6, v253, 36
	v_readlane_b32 s5, v253, 35
	v_lshl_add_u32 v64, v64, 2, 0
	v_add_u32_e32 v64, 0x21800, v64
	s_waitcnt vmcnt(1)
	v_mov_b32_e32 v74, v67
	v_mov_b32_e32 v75, v68
	v_mov_b32_e32 v67, v69
	v_pk_add_f32 v[66:67], v[74:75], v[66:67]
	s_waitcnt vmcnt(0)
	v_mov_b32_e32 v68, v72
	v_mov_b32_e32 v69, v70
	v_mov_b32_e32 v70, v73
	v_pk_add_f32 v[68:69], v[68:69], v[70:71]
	v_add_f32_e32 v65, v66, v67
	v_add_f32_e32 v65, v65, v69
	v_add_f32_e32 v65, v68, v65
	v_fmamk_f32 v65, v65, 0x3a800000, v190
	v_cmp_gt_f32_e32 vcc, s4, v65
	v_mul_f32_e32 v66, 0x4f800000, v65
	s_nop 0
	v_cndmask_b32_e32 v65, v65, v66, vcc
	v_sqrt_f32_e32 v66, v65
	s_nop 0
	v_add_u32_e32 v67, -1, v66
	v_fma_f32 v68, -v67, v66, v65
	v_cmp_ge_f32_e64 s[6:7], 0, v68
	v_add_u32_e32 v68, 1, v66
	s_nop 0
	v_cndmask_b32_e64 v67, v66, v67, s[6:7]
	v_fma_f32 v66, -v68, v66, v65
	v_cmp_lt_f32_e64 s[6:7], 0, v66
	s_nop 1
	v_cndmask_b32_e64 v66, v67, v68, s[6:7]
	v_mul_f32_e32 v67, 0x37800000, v66
	v_cndmask_b32_e32 v66, v66, v67, vcc
	v_cmp_class_f32_e32 vcc, v65, v192
	s_nop 1
	v_cndmask_b32_e32 v65, v66, v65, vcc
	v_div_scale_f32 v66, s[4:5], v65, v65, 1.0
	v_rcp_f32_e32 v67, v66
	s_nop 0
	v_fma_f32 v68, -v66, v67, 1.0
	v_fmac_f32_e32 v67, v68, v67
	v_div_scale_f32 v68, vcc, 1.0, v65, 1.0
	v_mul_f32_e32 v69, v68, v67
	v_fma_f32 v70, -v66, v69, v68
	v_fmac_f32_e32 v69, v70, v67
	v_fma_f32 v66, -v66, v69, v68
	v_div_fmas_f32 v66, v66, v67, v69
	v_div_fixup_f32 v65, v66, v65, 1.0
	ds_write_b32 v64, v65
